# static s_setprio 1 for waves 4-7 during the attention queue (on top of the per-tile stagger)
# baseline (speedup 1.0000x reference)
.LBB0_347:
	s_cmp_lt_u32 s99, 0x100
	s_cbranch_scc1 .Lprio_skip
	s_setprio 1

.LBB0_602:
	s_setprio 0
	s_cmp_gt_i32 s30, 5
	s_cselect_b64 s[0:1], -1, 0
	s_cmp_lt_i32 s31, 6
	s_cselect_b64 s[2:3], -1, 0
	s_or_b64 s[0:1], s[0:1], s[2:3]
	s_and_b64 vcc, exec, s[0:1]
	s_cbranch_vccnz .LBB0_673
	s_waitcnt vmcnt(0)
	s_waitcnt vmcnt(0) lgkmcnt(0)
	s_barrier
	s_and_saveexec_b64 s[0:1], s[14:15]
	s_cbranch_execz .LBB0_655
	s_add_i32 s2, 0, 0x20000
	v_mov_b32_e32 v0, s2
	s_waitcnt vmcnt(0) expcnt(0) lgkmcnt(0)
	ds_read_b32 v2, v0
	s_add_i32 s2, 0, 0x20004
	v_mov_b32_e32 v0, s2
	ds_read_b32 v0, v0
	s_waitcnt lgkmcnt(1)
	v_cmp_ne_u32_e32 vcc, 0, v2
	s_cbranch_vccnz .LBB0_619
	v_readlane_b32 s2, v242, 0
	s_mul_i32 s17, s91, s2
	s_add_u32 s2, s26, 0x3c00200
	s_addc_u32 s3, s27, 0
	s_add_u32 s4, s26, 0x3c00400
	s_addc_u32 s5, s27, 0
	s_add_u32 s6, s26, 0x3c00500
	s_addc_u32 s7, s27, 0
	s_add_u32 s8, s26, 0x3c00600
	s_addc_u32 s9, s27, 0
	s_add_u32 s10, s26, 0x3c00700
	s_addc_u32 s11, s27, 0
	s_add_u32 s12, s26, 0x3c00800
	s_addc_u32 s13, s27, 0
	s_add_u32 s42, s26, 0x3c00900
	s_addc_u32 s43, s27, 0
	s_add_u32 s44, s26, 0x3c00a00
	s_addc_u32 s45, s27, 0
	s_add_u32 s46, s26, 0x3c00b00
	s_addc_u32 s47, s27, 0
	s_add_u32 s48, s26, 0x3c00c00
	s_addc_u32 s49, s27, 0
	s_add_u32 s50, s26, 0x3c00d00
	s_addc_u32 s51, s27, 0
	s_add_u32 s52, s26, 0x3c00e00
	s_addc_u32 s53, s27, 0
	s_add_u32 s54, s26, 0x3c00f00
	s_addc_u32 s55, s27, 0
	s_add_u32 s56, s26, 0x3c01000
	s_addc_u32 s57, s27, 0
	s_add_u32 s58, s26, 0x3c01100
	s_addc_u32 s59, s27, 0
	s_add_u32 s60, s26, 0x3c01200
	s_addc_u32 s61, s27, 0
	s_add_u32 s62, s26, 0x3c01300
	s_mul_i32 s17, s17, s90
	s_addc_u32 s63, s27, 0
	s_mov_b32 s82, 1
	v_mov_b32_e32 v16, 0
	s_branch .LBB0_607
